# P2: next unit's expert-table row prefetched during attention compute (A units), tab_finish overlaps K/V loads, DPP row-max; attention cross-half max via permlane32_swap; P7c reductions via permlane/DP
# speedup vs baseline: 1.0185x; 1.0185x over previous
; #define TAB_ROW(s) ((((s) & 8) ? 16384 : 0) + (TAB_VW(s) >> 1) * 16 + (TAB_VW(s) & 1) * 8 + ((s) & 7))
; __device__ __forceinline__ void tab_load(const Frame& F, int row, int lane, f32x4 (&t)[8]) {
;     const float* s0 = (row < 16384 ? F.expert_u + (size_t)row * DM : F.expert_v + (size_t)(row - 16384) * DM) + 16 * lane;
; #pragma unroll
;     for (int q = 0; q < 8; ++q) t[q] = *(const f32x4*)(s0 + 1024 * (q >> 2) + 4 * (q & 3));
; }
; template <int MODE  >
; __device__ __forceinline__ void p2_attention(Frame& F) {
;     ...
;         if (TAB_P2 && MODE == 0 && TAB_VW(k) < 2048) {
;             f32x4 trow[8]; const int row = TAB_ROW(k);
;             tab_load(F, row, lane, trow);
;             __syncthreads();
;             ATT_LOADKV(cur); tab_finish(F, row, lane, trow, gl); ATT_WRITEKV(cur);
.LBB0_265:
	s_mov_b64 s[0:1], 0
	s_cbranch_execz .LBB0_304
	v_readlane_b32 s6, v254, 51
	s_lshl_b32 s0, s6, 11
	s_lshl_b32 s1, s15, 3
	s_and_b32 s0, s0, 0x4000
	s_and_b32 s19, s1, -16
	s_add_i32 s19, s19, s0
	s_and_b32 s0, s6, 7
	v_readlane_b32 s1, v254, 53
	s_or_b32 s18, s0, s1
	s_or_b32 s16, s19, s18
	s_cmpk_lt_i32 s16, 0x4000
	s_cselect_b64 s[6:7], -1, 0
	s_cmpk_gt_i32 s16, 0x3fff
	v_readlane_b32 s0, v254, 49
	s_cselect_b64 s[10:11], -1, 0
	v_readlane_b32 s1, v254, 50
	s_add_i32 s20, s16, 0xffffc000
	s_ashr_i32 s8, s16, 31
	s_mov_b32 s21, s1
	s_and_b64 s[0:1], s[6:7], exec
	s_cselect_b32 s1, s8, 0
	v_writelane_b32 v254, s20, 49
	s_cselect_b32 s0, s16, s20
	s_cselect_b32 s8, s67, s69
	s_cselect_b32 s9, s66, s68
	s_lshl_b64 s[0:1], s[0:1], 13
	s_add_u32 s0, s9, s0
	v_lshlrev_b32_e32 v102, 4, v104
	s_addc_u32 s1, s8, s1
	v_ashrrev_i32_e32 v103, 31, v102
	v_readlane_b32 s98, v254, 51
	s_nop 3
	s_cmp_gt_u32 s98, 3
	s_cbranch_scc1 .Lpf_copy
	s_waitcnt vmcnt(1)
	v_lshl_add_u64 v[2:3], v[102:103], 2, s[0:1]
	s_mov_b64 s[0:1], 0x1000
	v_lshl_add_u64 v[4:5], v[2:3], 0, s[0:1]
	s_movk_i32 s0, 0x1000
	global_load_dwordx4 v[54:57], v[2:3], off offset:48
	global_load_dwordx4 v[62:65], v[2:3], off offset:32
	global_load_dwordx4 v[70:73], v[2:3], off offset:16
	global_load_dwordx4 v[82:85], v[2:3], off
	global_load_dwordx4 v[46:49], v[4:5], off
	global_load_dwordx4 v[18:21], v[4:5], off offset:48
	global_load_dwordx4 v[26:29], v[4:5], off offset:32
	global_load_dwordx4 v[38:41], v[4:5], off offset:16
	s_branch .Lpf_top_done
.Lpf_copy:
	s_waitcnt vmcnt(9)
	v_mov_b64_e32 v[82:83], v[152:153]
	v_mov_b64_e32 v[84:85], v[154:155]
	v_mov_b64_e32 v[70:71], v[156:157]
	v_mov_b64_e32 v[72:73], v[158:159]
	v_mov_b64_e32 v[62:63], v[160:161]
	v_mov_b64_e32 v[64:65], v[162:163]
	v_mov_b64_e32 v[54:55], v[164:165]
	v_mov_b64_e32 v[56:57], v[166:167]
	v_mov_b64_e32 v[46:47], v[168:169]
	v_mov_b64_e32 v[48:49], v[170:171]
	v_mov_b64_e32 v[38:39], v[172:173]
	v_mov_b64_e32 v[40:41], v[174:175]
	v_mov_b64_e32 v[26:27], v[196:197]
	v_mov_b64_e32 v[28:29], v[198:199]
	v_mov_b64_e32 v[18:19], v[200:201]
	v_mov_b64_e32 v[20:21], v[202:203]
.Lpf_top_done:
	v_add_co_u32_e32 v2, vcc, s0, v2
	s_and_b64 s[0:1], s[2:3], exec
	s_nop 0
	v_addc_co_u32_e32 v3, vcc, 0, v3, vcc
	s_movk_i32 s0, 0x180
	s_cselect_b32 s17, s0, 0x200
	s_movk_i32 s0, 0xff80
	v_writelane_b32 v254, s21, 50
	s_cselect_b32 s20, 0xffffffc0, s0
	s_ashr_i32 s0, s12, 6
	s_add_i32 s20, s20, s13
	s_mul_hi_i32 s1, s0, 0x300000
	s_mul_i32 s0, s0, 0x300000
	s_add_u32 s12, s82, s0
	s_addc_u32 s13, s83, s1
	s_ashr_i32 s0, s14, 6
	s_mul_hi_i32 s1, s0, 0x300000
	s_mul_i32 s0, s0, 0x300000
	s_add_u32 s14, s82, s0
	v_add_u32_e32 v2, s20, v107
	s_addc_u32 s15, s83, s1
	v_cmp_gt_i32_e32 vcc, s17, v107
	v_cmp_lt_i32_e64 s[0:1], -1, v2
	s_and_b64 s[0:1], vcc, s[0:1]
	v_cmp_gt_i32_e32 vcc, s88, v2
	v_and_b32_e32 v103, 56, v105
	s_and_b64 s[8:9], s[0:1], vcc
	v_mov_b32_e32 v6, 0
	v_mov_b32_e32 v10, 0
	v_mov_b32_e32 v11, 0
	v_mov_b32_e32 v12, 0
	v_mov_b32_e32 v13, 0
	s_waitcnt vmcnt(8)
	v_mov_b32_e32 v14, 0
	v_mov_b32_e32 v15, 0
	v_mov_b32_e32 v16, 0
	v_mov_b32_e32 v17, 0
	s_waitcnt lgkmcnt(0)
	s_barrier
	s_and_saveexec_b64 s[0:1], s[8:9]
	s_cbranch_execz .LBB0_268
	v_mul_lo_u32 v2, v2, s90
	v_add_u32_e32 v2, s33, v2
	v_ashrrev_i32_e32 v3, 31, v2
	v_lshlrev_b64 v[2:3], 7, v[2:3]
	v_lshl_or_b32 v2, v103, 1, v2
	v_lshl_add_u64 v[4:5], s[12:13], 0, v[2:3]
	v_lshl_add_u64 v[2:3], s[14:15], 0, v[2:3]
	global_load_dwordx4 v[10:13], v[4:5], off
	global_load_dwordx4 v[14:17], v[2:3], off

; #define LAS __attribute__((address_space(3)))
; __device__ __forceinline__ void tab_finish(const Frame& F, int row, int lane, const f32x4 (&t)[8], const LAS float* gl  ) {
;     const bool isu = row < 16384; const int e = isu ? row : row - 16384;
;     float v[32]; float am = 0.f;
;     if (isu) {
; #pragma unroll
;         for (int q = 0; q < 8; ++q) { const f32x4 g = *(const LAS f32x4*)(gl + 1024 * (q >> 2) + 16 * lane + 4 * (q & 3));
; #pragma unroll
;             for (int c = 0; c < 4; ++c) { const float x = t[q][c] * g[c]; v[4 * q + c] = x; am = fmaxf(am, fabsf(x)); } } }
;     else {
; #pragma unroll
;         for (int q = 0; q < 8; ++q)
; #pragma unroll
;             for (int c = 0; c < 4; ++c) { const float x = t[q][c]; v[4 * q + c] = x; am = fmaxf(am, fabsf(x)); } }
.LBB0_282:
	s_or_b64 exec, exec, s[0:1]
	v_readlane_b32 s98, v254, 51
	s_nop 3
	s_cmp_gt_u32 s98, 3
	s_cbranch_scc1 .Lpf_nowait
	s_waitcnt vmcnt(0)
.Lpf_nowait:
	s_mov_b64 s[0:1], -1
	s_and_b64 vcc, exec, s[10:11]
	s_cbranch_vccz .LBB0_285
	v_max_f32_e64 v103, |v82|, |v82|
	v_max_f32_e32 v103, 0, v103
	v_max3_f32 v103, v103, |v83|, |v84|
	v_max3_f32 v103, v103, |v85|, |v70|
	v_max3_f32 v103, v103, |v71|, |v72|
	v_max3_f32 v103, v103, |v73|, |v62|
	v_max3_f32 v103, v103, |v63|, |v64|
	v_max3_f32 v103, v103, |v65|, |v54|
	v_max3_f32 v103, v103, |v55|, |v56|
	v_max3_f32 v103, v103, |v57|, |v46|
	v_max3_f32 v103, v103, |v47|, |v48|
	v_max3_f32 v103, v103, |v49|, |v38|
	v_max3_f32 v103, v103, |v39|, |v40|
	v_max3_f32 v103, v103, |v41|, |v26|
	v_max3_f32 v103, v103, |v27|, |v28|
	v_max3_f32 v103, v103, |v29|, |v18|
	v_max3_f32 v103, v103, |v19|, |v20|
	s_cbranch_execz .LBB0_286

; #define LAS __attribute__((address_space(3)))
; __device__ __forceinline__ void tab_finish(const Frame& F, int row, int lane, const f32x4 (&t)[8], const LAS float* gl  ) {
;     ...
;     if (isu) {
; #pragma unroll
;         for (int q = 0; q < 8; ++q) { const f32x4 g = *(const LAS f32x4*)(gl + 1024 * (q >> 2) + 16 * lane + 4 * (q & 3));
; #pragma unroll
;             for (int c = 0; c < 4; ++c) { const float x = t[q][c] * g[c]; v[4 * q + c] = x; am = fmaxf(am, fabsf(x)); } } }
;     else {
; #pragma unroll
;         for (int q = 0; q < 8; ++q)
; #pragma unroll
;             for (int c = 0; c < 4; ++c) { const float x = t[q][c]; v[4 * q + c] = x; am = fmaxf(am, fabsf(x)); } }
; #pragma unroll
;     for (int o = 1; o < 64; o <<= 1) am = fmaxf(am, __shfl_xor(am, o));
;     const float inv = am > 0.f ? 127.0f / am : 0.f;
;     unsigned char* U = F.ws + WS_U; unsigned char* V = F.ws + WS_V;
; #pragma unroll
;     for (int j = 0; j < 2; ++j) { v4u o;
; #pragma unroll
;         for (int q = 0; q < 4; ++q) { unsigned w = 0;
; #pragma unroll
;             for (int c = 0; c < 4; ++c) { const int qi = (int)__builtin_rintf(v[16 * j + 4 * q + c] * inv); w |= ((unsigned)qi & 0xffu) << (8 * c); }
;             o[q] = w; }
.LBB0_286:
	v_lshl_add_u32 v103, v104, 6, 0
	v_add_u32_e32 v103, 0x20400, v103
	ds_read_b128 v[108:111], v103
	ds_read_b128 v[112:115], v103 offset:16
	ds_read_b128 v[116:119], v103 offset:32
	ds_read_b128 v[120:123], v103 offset:48
	s_mov_b64 s[0:1], 22
	s_waitcnt lgkmcnt(3)
	v_pk_mul_f32 v[82:83], v[82:83], v[108:109]
	v_pk_mul_f32 v[84:85], v[84:85], v[110:111]
	v_max_f32_e64 v108, |v82|, 0
	v_max3_f32 v108, v108, |v83|, |v84|
	s_waitcnt lgkmcnt(2)
	v_pk_mul_f32 v[70:71], v[70:71], v[112:113]
	v_pk_mul_f32 v[72:73], v[72:73], v[114:115]
	v_max3_f32 v108, v108, |v85|, |v70|
	v_max3_f32 v108, v108, |v71|, |v72|
	s_waitcnt lgkmcnt(1)
	v_pk_mul_f32 v[62:63], v[62:63], v[116:117]
	v_pk_mul_f32 v[64:65], v[64:65], v[118:119]
	v_max3_f32 v108, v108, |v73|, |v62|
	v_max3_f32 v112, v108, |v63|, |v64|
	ds_read_b128 v[108:111], v103 offset:4096
	s_waitcnt lgkmcnt(1)
	v_pk_mul_f32 v[54:55], v[54:55], v[120:121]
	v_pk_mul_f32 v[56:57], v[56:57], v[122:123]
	v_max3_f32 v112, v112, |v65|, |v54|
	v_max3_f32 v116, v112, |v55|, |v56|
	ds_read_b128 v[112:115], v103 offset:4112
	s_waitcnt lgkmcnt(1)
	v_pk_mul_f32 v[46:47], v[46:47], v[108:109]
	v_pk_mul_f32 v[48:49], v[48:49], v[110:111]
	v_max3_f32 v108, v116, |v57|, |v46|
	v_max3_f32 v116, v108, |v47|, |v48|
	ds_read_b128 v[108:111], v103 offset:4128
	s_waitcnt lgkmcnt(1)
	v_pk_mul_f32 v[38:39], v[38:39], v[112:113]
	v_pk_mul_f32 v[40:41], v[40:41], v[114:115]
	v_max3_f32 v112, v116, |v49|, |v38|
	v_max3_f32 v116, v112, |v39|, |v40|
	ds_read_b128 v[112:115], v103 offset:4144
	s_waitcnt lgkmcnt(1)
	v_pk_mul_f32 v[26:27], v[26:27], v[108:109]
	v_pk_mul_f32 v[28:29], v[28:29], v[110:111]
	v_max3_f32 v103, v116, |v41|, |v26|
	v_max3_f32 v103, v103, |v27|, |v28|
	s_waitcnt lgkmcnt(0)
	v_pk_mul_f32 v[18:19], v[18:19], v[112:113]
	v_pk_mul_f32 v[20:21], v[20:21], v[114:115]
	v_max3_f32 v103, v103, |v29|, |v18|
	v_max3_f32 v103, v103, |v19|, |v20|
	s_mov_b64 s[8:9], 0x2700000
.LBB0_287:
	v_max_f32_e64 v108, |v21|, |v21|
	v_max_f32_e32 v103, v103, v103
	v_max_f32_e32 v103, v103, v108
	s_mov_b32 s1, 0x42fe0000
	v_readlane_b32 s12, v255, 9
	v_readlane_b32 s13, v255, 10
	v_ashrrev_i32_e32 v115, 3, v104
	v_mov_b32_e32 v113, v0
	s_nop 1
	v_max_f32_dpp v103, v103, v103 quad_perm:[1,0,3,2] row_mask:0xf bank_mask:0xf
	s_nop 1
	v_max_f32_dpp v103, v103, v103 quad_perm:[2,3,0,1] row_mask:0xf bank_mask:0xf
	s_nop 1
	v_max_f32_dpp v103, v103, v103 row_half_mirror row_mask:0xf bank_mask:0xf
	s_nop 1
	v_max_f32_dpp v103, v103, v103 row_mirror row_mask:0xf bank_mask:0xf
	v_mov_b32_e32 v109, v103
	s_nop 1
	v_permlane16_swap_b32_e32 v103, v109
	v_max_f32_e32 v103, v103, v109
	v_mov_b32_e32 v109, v103
	s_nop 1
	v_permlane32_swap_b32_e32 v103, v109
	v_max_f32_e32 v103, v103, v109
	v_div_scale_f32 v108, s[10:11], v103, v103, s1
	v_rcp_f32_e32 v109, v108
	v_div_scale_f32 v110, vcc, s1, v103, s1
	v_readlane_b32 s10, v254, 49
	v_fma_f32 v111, -v108, v109, 1.0
	v_fmac_f32_e32 v109, v111, v109
	v_mul_f32_e32 v111, v110, v109
	v_fma_f32 v112, -v108, v111, v110
	v_fmac_f32_e32 v111, v112, v109
	v_fma_f32 v108, -v108, v111, v110
	v_div_fmas_f32 v108, v108, v109, v111
	v_div_fixup_f32 v108, v108, v103, s1
	v_cmp_lt_f32_e32 vcc, 0, v103
	v_readlane_b32 s11, v254, 50
	s_lshl_b64 s[10:11], s[10:11], 7
	v_cndmask_b32_e32 v114, 0, v108, vcc
	v_mul_f32_e32 v19, v19, v114
	v_mul_f32_e32 v55, v55, v114
	v_mul_f32_e32 v18, v18, v114
	v_rndne_f32_e32 v19, v19
	v_mul_f32_e32 v20, v20, v114
	v_mul_f32_e32 v21, v21, v114
	v_mul_f32_e32 v54, v54, v114
	v_rndne_f32_e32 v55, v55
	v_mul_f32_e32 v56, v56, v114
	v_mul_f32_e32 v57, v57, v114
	v_mul_f32_e32 v46, v46, v114
	v_mul_f32_e32 v49, v49, v114
	v_rndne_f32_e32 v18, v18
	v_cvt_i32_f32_e32 v19, v19
	v_rndne_f32_e32 v20, v20
	v_rndne_f32_e32 v21, v21
	s_add_u32 s10, s12, s10
	v_mul_f32_e32 v82, v82, v114
	v_mul_f32_e32 v85, v85, v114
	v_rndne_f32_e32 v54, v54
	v_cvt_i32_f32_e32 v55, v55
	v_rndne_f32_e32 v56, v56
	v_rndne_f32_e32 v57, v57
	v_rndne_f32_e32 v46, v46
	v_rndne_f32_e32 v49, v49
	v_cvt_i32_f32_e32 v18, v18
	v_cvt_i32_f32_sdwa v20, v20 dst_sel:WORD_1 dst_unused:UNUSED_PAD src0_sel:DWORD
	v_cvt_i32_f32_e32 v21, v21
	s_addc_u32 s11, s13, s11
	v_and_b32_e32 v108, 0x70, v102
	v_mov_b32_e32 v109, v0
	v_rndne_f32_e32 v82, v82
	v_rndne_f32_e32 v85, v85
	v_cvt_i32_f32_e32 v54, v54
	v_cvt_i32_f32_sdwa v56, v56 dst_sel:WORD_1 dst_unused:UNUSED_PAD src0_sel:DWORD
	v_cvt_i32_f32_e32 v57, v57
	v_cvt_i32_f32_e32 v46, v46
	v_cvt_i32_f32_e32 v49, v49
	v_lshl_add_u64 v[108:109], s[10:11], 0, v[108:109]
	s_ashr_i32 s10, s19, 4
	v_cvt_i32_f32_e32 v82, v82
	v_mul_f32_e32 v83, v83, v114
	v_cvt_i32_f32_e32 v85, v85
	v_mul_f32_e32 v71, v71, v114
	v_mul_f32_e32 v63, v63, v114
	v_mul_f32_e32 v47, v47, v114
	v_mul_f32_e32 v39, v39, v114
	v_mul_f32_e32 v27, v27, v114
	s_ashr_i32 s11, s10, 31
	v_rndne_f32_e32 v83, v83
	v_mul_f32_e32 v84, v84, v114
	s_mov_b32 s1, 0x40c0c00
	v_mul_f32_e32 v70, v70, v114
	v_rndne_f32_e32 v71, v71
	v_mul_f32_e32 v72, v72, v114
	v_mul_f32_e32 v73, v73, v114
; __device__ __forceinline__ void tab_finish(const Frame& F, int row, int lane, const f32x4 (&t)[8], const LAS float* gl  ) {
;     ...
;     for (int j = 0; j < 2; ++j) { v4u o;
; #pragma unroll
;         for (int q = 0; q < 4; ++q) { unsigned w = 0;
; #pragma unroll
;             for (int c = 0; c < 4; ++c) { const int qi = (int)__builtin_rintf(v[16 * j + 4 * q + c] * inv); w |= ((unsigned)qi & 0xffu) << (8 * c); }
;             o[q] = w; }
;         if (isu) { const int cidx = lane + 64 * j;
;             *(v4u*)(U + (size_t)(cidx >> 4) * (1024 * 4096) + (size_t)(e >> 4) * 4096 + ((cidx & 15) >> 2) * 1024 + (((cidx & 3) << 4) + (e & 15)) * 16) = o; }
;         else *(v4u*)(V + (size_t)e * 128 + (size_t)((lane >> 3) + 8 * j) * (16384 * 128) + 16 * (lane & 7)) = o; }
;     if (lane == 0) ((float*)(F.ws + (isu ? WS_US : WS_VS)))[e] = am > 0.f ? am * (1.0f / 127.0f) : 1.0f;
	v_mul_f32_e32 v62, v62, v114
	v_rndne_f32_e32 v63, v63
	v_mul_f32_e32 v64, v64, v114
	v_mul_f32_e32 v65, v65, v114
	v_rndne_f32_e32 v47, v47
	v_mul_f32_e32 v48, v48, v114
	v_mul_f32_e32 v38, v38, v114
	v_rndne_f32_e32 v39, v39
	v_mul_f32_e32 v40, v40, v114
	v_mul_f32_e32 v41, v41, v114
	v_mul_f32_e32 v26, v26, v114
	v_rndne_f32_e32 v27, v27
	v_mul_f32_e32 v28, v28, v114
	v_mul_f32_e32 v29, v29, v114
	v_lshlrev_b32_e32 v19, 8, v19
	s_lshl_b64 s[10:11], s[10:11], 12
	v_readlane_b32 s12, v255, 7
	v_cvt_i32_f32_e32 v83, v83
	v_rndne_f32_e32 v84, v84
	v_rndne_f32_e32 v70, v70
	v_cvt_i32_f32_e32 v71, v71
	v_rndne_f32_e32 v72, v72
	v_rndne_f32_e32 v73, v73
	v_rndne_f32_e32 v62, v62
	v_cvt_i32_f32_e32 v63, v63
	v_rndne_f32_e32 v64, v64
	v_rndne_f32_e32 v65, v65
	v_lshlrev_b32_e32 v55, 8, v55
	v_cvt_i32_f32_e32 v47, v47
	v_rndne_f32_e32 v48, v48
	v_rndne_f32_e32 v38, v38
	v_cvt_i32_f32_e32 v39, v39
	v_rndne_f32_e32 v40, v40
	v_rndne_f32_e32 v41, v41
	v_rndne_f32_e32 v26, v26
	v_cvt_i32_f32_e32 v27, v27
	v_rndne_f32_e32 v28, v28
	v_rndne_f32_e32 v29, v29
	v_and_b32_e32 v19, 0xff00, v19
	v_and_b32_e32 v20, 0xff0000, v20
	v_perm_b32 v18, v21, v18, s1
	v_readlane_b32 s13, v255, 8
	s_add_u32 s10, s12, s10
	v_lshlrev_b32_e32 v110, 8, v104
	v_cvt_i32_f32_sdwa v84, v84 dst_sel:WORD_1 dst_unused:UNUSED_PAD src0_sel:DWORD
	v_cvt_i32_f32_e32 v70, v70
	v_cvt_i32_f32_sdwa v72, v72 dst_sel:WORD_1 dst_unused:UNUSED_PAD src0_sel:DWORD
	v_cvt_i32_f32_e32 v73, v73
	v_cvt_i32_f32_e32 v62, v62
	v_cvt_i32_f32_sdwa v64, v64 dst_sel:WORD_1 dst_unused:UNUSED_PAD src0_sel:DWORD
	v_cvt_i32_f32_e32 v65, v65
	v_and_b32_e32 v55, 0xff00, v55
	v_and_b32_e32 v56, 0xff0000, v56
	v_perm_b32 v54, v57, v54, s1
	v_cvt_i32_f32_sdwa v48, v48 dst_sel:WORD_1 dst_unused:UNUSED_PAD src0_sel:DWORD
	v_perm_b32 v46, v49, v46, s1
	v_cvt_i32_f32_e32 v38, v38
	v_cvt_i32_f32_sdwa v40, v40 dst_sel:WORD_1 dst_unused:UNUSED_PAD src0_sel:DWORD
	v_cvt_i32_f32_e32 v41, v41
	v_cvt_i32_f32_e32 v26, v26
	v_cvt_i32_f32_sdwa v28, v28 dst_sel:WORD_1 dst_unused:UNUSED_PAD src0_sel:DWORD
	v_cvt_i32_f32_e32 v29, v29
	v_or3_b32 v49, v18, v19, v20
	v_add_u32_e32 v18, 64, v104
	s_addc_u32 s11, s13, s11
	v_and_b32_e32 v110, 0xc00, v110
	v_mov_b32_e32 v111, v0
	v_and_or_b32 v102, v102, 48, s18
	v_perm_b32 v82, v85, v82, s1
	v_or3_b32 v85, v54, v55, v56
	v_ashrrev_i32_e32 v54, 4, v104
	v_ashrrev_i32_e32 v18, 4, v18
	v_add_u32_e32 v19, 8, v115
	v_lshl_add_u64 v[110:111], s[10:11], 0, v[110:111]
	v_lshlrev_b32_e32 v112, 4, v102
	v_cndmask_b32_e64 v54, v115, v54, s[6:7]
	v_cndmask_b32_e64 v18, v19, v18, s[6:7]
	v_lshl_add_u64 v[110:111], v[110:111], 0, v[112:113]
	v_lshlrev_b32_e32 v83, 8, v83
	v_lshlrev_b32_e32 v71, 8, v71
	v_lshlrev_b32_e32 v63, 8, v63
	v_ashrrev_i32_e32 v55, 31, v54
	v_lshlrev_b32_e32 v47, 8, v47
	v_lshlrev_b32_e32 v39, 8, v39
	v_lshlrev_b32_e32 v27, 8, v27
	v_ashrrev_i32_e32 v19, 31, v18
	v_and_b32_e32 v83, 0xff00, v83
	v_and_b32_e32 v84, 0xff0000, v84
	v_and_b32_e32 v71, 0xff00, v71
	v_and_b32_e32 v72, 0xff0000, v72
	v_perm_b32 v70, v73, v70, s1
	v_and_b32_e32 v63, 0xff00, v63
	v_and_b32_e32 v64, 0xff0000, v64
	v_perm_b32 v62, v65, v62, s1
	v_cndmask_b32_e64 v57, v109, v111, s[6:7]
	v_cndmask_b32_e64 v56, v108, v110, s[6:7]
	v_lshlrev_b64 v[54:55], s0, v[54:55]
	v_and_b32_e32 v47, 0xff00, v47
	v_and_b32_e32 v48, 0xff0000, v48
	v_and_b32_e32 v39, 0xff00, v39
	v_and_b32_e32 v40, 0xff0000, v40
	v_perm_b32 v38, v41, v38, s1
	v_and_b32_e32 v27, 0xff00, v27
	v_and_b32_e32 v28, 0xff0000, v28
	v_perm_b32 v26, v29, v26, s1
	v_lshlrev_b64 v[18:19], s0, v[18:19]
	v_or3_b32 v82, v82, v83, v84
	v_or3_b32 v83, v70, v71, v72
	v_or3_b32 v84, v62, v63, v64
	v_lshl_add_u64 v[54:55], v[56:57], 0, v[54:55]
	v_or3_b32 v46, v46, v47, v48
	v_or3_b32 v47, v38, v39, v40
	v_or3_b32 v48, v26, v27, v28
	v_lshl_add_u64 v[18:19], v[56:57], 0, v[18:19]
	v_cmp_eq_u32_e64 s[0:1], 0, v104
	global_store_dwordx4 v[54:55], v[82:85], off
	global_store_dwordx4 v[18:19], v[46:49], off
	s_and_saveexec_b64 s[10:11], s[0:1]
	s_cbranch_execz .LBB0_289
	s_and_b64 s[0:1], s[6:7], exec
	v_readlane_b32 s0, v254, 49
	v_readlane_b32 s1, v254, 50
	s_cselect_b32 s0, s16, s0
	s_add_u32 s6, s74, s8
	s_addc_u32 s7, s75, s9
	s_ashr_i32 s1, s0, 31
	s_lshl_b64 s[0:1], s[0:1], 2
	s_add_u32 s0, s6, s0
	v_mul_f32_e32 v18, 0x3c010204, v103
	s_addc_u32 s1, s7, s1
	v_cndmask_b32_e32 v18, 1.0, v18, vcc
	global_store_dword v0, v18, s[0:1]
.LBB0_289:
	s_or_b64 exec, exec, s[10:11]
	s_waitcnt vmcnt(3)
	v_ashrrev_i32_e32 v20, 4, v106
	v_and_b32_e32 v18, 7, v104
	v_xor_b32_e32 v21, v20, v104
	v_lshlrev_b32_e32 v20, 2, v20
	v_bitop3_b32 v18, v20, v18, 4 bitop3:0x6c
	v_lshlrev_b32_e32 v19, 7, v107
	v_lshlrev_b32_e32 v21, 4, v21
	v_lshlrev_b32_e32 v18, 4, v18
	v_readlane_b32 s0, v255, 11
	v_and_b32_e32 v21, 0x70, v21
	v_add3_u32 v70, 0, v19, v21
	v_add3_u32 v71, s0, v19, v18
	v_sub_u32_e32 v18, s17, v107
	v_cmp_lt_i32_e32 vcc, 0, v18
	s_and_saveexec_b64 s[0:1], vcc
	s_cbranch_execz .LBB0_291
	ds_write_b128 v70, v[10:13]
	ds_write_b128 v71, v[14:17]

; #define LAS __attribute__((address_space(3)))
;     constexpr int NTILE = 1 + 2 * HALFW / 32, JM = HALFW / 32;
;     const int ql = lane & 31, hh = lane >> 5;
;     o0 = (f32x16){}; o1 = (f32x16){};
;     float m = -1e30f, lsum = 0.f;
;     const int i15 = lane & 15, G = (lane >> 4) & 1, ql4 = ql - 4 * hh;
;     f32x16 CL, CM, CR;
;     { const float sq = slope2 * (float)ql;
; #pragma unroll
;       for (int reg = 0; reg < 16; ++reg) { const float kb_ = slope2 * (float)((reg & 3) + 8 * (reg >> 2) + 4 * hh); CL[reg] = kb_; CR[reg] = -kb_; CM[reg] = -fabsf(kb_ - sq); } }
;     const LAS unsigned char* kb = Ks + (LDSFLAT ? 0 : (32 * w + ql) * 128); const int sw = LDSFLAT ? 0 : ((ql >> 1) & 7);
;     int koff[4];
; #pragma unroll
;     for (int ks = 0; ks < 4; ++ks) koff[ks] = LDSFLAT ? 0 : (((2 * ks + hh) ^ sw) << 4);
;     const int c0 = (2 * G + ((i15 & 3) >> 1)) ^ (((i15 >> 3) & 1) << 2);
;     const LAS unsigned char* vb0 = LDSFLAT ? Vs : Vs + (32 * w + 4 * hh + (i15 >> 2)) * 128 + (i15 & 1) * 8 + (c0 << 4);
;     const LAS unsigned char* vb1 = LDSFLAT ? Vs + 64 : Vs + (32 * w + 4 * hh + (i15 >> 2)) * 128 + (i15 & 1) * 8 + ((c0 ^ 4) << 4);
;     bf16x8 kf[4];
; #pragma unroll
;     for (int ks = 0; ks < 4; ++ks) kf[ks] = *(const LAS bf16x8*)(kb + koff[ks]);
; template <int MODE  >
; __device__ __forceinline__ void p2_attention(Frame& F) {
;     ...
;                 const float slope = exp2f(-0.25f * (float)(2 * cur.head + 1));
;                 att_wave<64, MODE == 6>(ln, w, Ks, Vs, cur.q0 - 64 + 32 * w, cur.Lsub, qc, slope * (float)cur.d * LOG2E, o0, o1, m, l, MODE == 5 ? 2 : 0, MODE == 5 ? 3 : 5);
.LBB0_306:
	s_or_b64 exec, exec, s[6:7]
	s_waitcnt vmcnt(1)
	v_lshlrev_b64 v[2:3], 6, v[98:99]
	v_lshl_add_u64 v[2:3], v[2:3], 1, s[82:83]
	v_lshl_add_u64 v[2:3], v[100:101], 1, v[2:3]
	s_add_i32 s5, s5, 1
	v_mov_b32_e32 v4, 0x300000
	s_xor_b64 s[42:43], s[2:3], -1
	v_mad_i64_i32 v[212:213], s[2:3], s5, v4, v[2:3]
	s_lshl_b32 s2, s40, 1
	s_or_b32 s2, s2, 1
	v_cvt_f32_i32_e32 v7, s2
	v_ashrrev_i32_e32 v2, 5, v104
	v_lshlrev_b32_e32 v3, 2, v2
	v_or_b32_e32 v5, 2, v3
	v_cvt_f32_i32_e32 v216, v5
	v_add_u32_e32 v5, 9, v3
	v_mul_f32_e32 v8, 0xbe800000, v7
	s_mov_b32 s2, 0xc2fc0000
	v_cvt_f32_i32_e32 v219, v5
	v_add_u32_e32 v5, 11, v3
	v_cmp_gt_f32_e32 vcc, s2, v8
	v_mov_b32_e32 v8, 0x42800000
	v_cvt_f32_i32_e32 v221, v5
	v_add_u32_e32 v5, 17, v3
	v_cndmask_b32_e32 v8, 0, v8, vcc
	v_or_b32_e32 v4, 1, v3
	v_cvt_f32_i32_e32 v223, v5
	v_add_u32_e32 v5, 19, v3
	v_fmac_f32_e32 v8, 0xbe800000, v7
	v_cvt_f32_i32_e32 v215, v4
	v_or_b32_e32 v4, 3, v3
	v_cvt_f32_i32_e32 v225, v5
	v_add_u32_e32 v5, 25, v3
	v_exp_f32_e32 v7, v8
	s_and_b64 s[2:3], vcc, exec
	v_cvt_f32_i32_e32 v217, v4
	v_add_u32_e32 v4, 8, v3
	v_cvt_f32_i32_e32 v227, v5
	v_add_u32_e32 v5, 27, v3
	v_cvt_f32_i32_e32 v8, s90
	s_mul_i32 s3, s58, 0x3000000
	v_cvt_f32_i32_e32 v218, v4
	v_add_u32_e32 v4, 10, v3
	v_cvt_f32_i32_e32 v229, v5
	v_lshrrev_b32_e32 v5, 1, v104
	s_cselect_b32 s62, 0xffffffc0, 0
	s_mul_hi_i32 s2, s58, 0x3000000
	s_add_u32 s59, s72, s3
	v_cvt_f32_i32_e32 v220, v4
	v_add_u32_e32 v4, 16, v3
	v_bitop3_b32 v6, v5, v2, 7 bitop3:0x6c
	s_addc_u32 s60, s73, s2
	s_lshl_b32 s2, s40, 6
	v_cvt_f32_i32_e32 v222, v4
	v_add_u32_e32 v4, 18, v3
	v_lshlrev_b32_e32 v237, 4, v6
	v_add_u32_e32 v6, 2, v2
	s_ashr_i32 s3, s2, 31
	v_ldexp_f32 v7, v7, s62
	v_cvt_f32_i32_e32 v224, v4
	v_add_u32_e32 v4, 24, v3
	v_bitop3_b32 v6, v6, v5, 7 bitop3:0x78
	s_lshl_b64 s[2:3], s[2:3], 1
	v_mul_f32_e32 v7, v7, v8
	v_cvt_f32_i32_e32 v226, v4
	v_add_u32_e32 v4, 26, v3
	v_lshlrev_b32_e32 v238, 4, v6
	v_add_u32_e32 v6, 4, v2
	v_add_u32_e32 v2, 6, v2
	s_add_u32 s2, s59, s2
	v_mul_f32_e32 v230, 0x3fb8aa3b, v7
	v_cvt_f32_ubyte0_e32 v236, v1
	v_cvt_f32_i32_e32 v228, v4
	v_or_b32_e32 v4, s77, v1
	v_bitop3_b32 v2, v2, v5, 7 bitop3:0x78
	s_addc_u32 s3, s60, s3
	s_waitcnt vmcnt(0)
	v_pk_mul_f32 v[18:19], v[230:231], v[216:217] op_sel_hi:[0,1]
	v_lshlrev_b32_e32 v240, 4, v2
	v_lshl_add_u32 v241, v4, 7, 0
	v_lshrrev_b32_e32 v2, 3, v104
	v_and_b32_e32 v4, 5, v5
	v_writelane_b32 v255, s2, 37
	v_fma_f32 v7, -v230, v236, v18
	v_cvt_f32_i32_e32 v214, v3
	v_bitop3_b32 v6, v6, v5, 7 bitop3:0x78
	v_and_or_b32 v2, v2, 2, v4
	v_bfe_u32 v5, v104, 2, 2
	v_writelane_b32 v255, s3, 38
	s_mul_hi_i32 s2, s58, 0x180000
	s_mul_i32 s58, s58, 0x180000
	v_readlane_b32 s3, v254, 55
	v_and_b32_e32 v48, 0x7fffffff, v7
	v_add_u32_e32 v7, s77, v3
	v_lshlrev_b32_e32 v2, 4, v2
	s_add_u32 s58, s3, s58
	v_readlane_b32 s3, v254, 57
	v_add_lshl_u32 v5, v7, v5, 7
	s_addc_u32 s59, s3, s2
	s_mov_b32 s2, s40
	v_bitop3_b32 v2, v2, v5, 64 bitop3:0xde
	s_ashr_i32 s41, s40, 31
	v_writelane_b32 v255, s2, 39
	v_add_u32_e32 v234, 0, v2
	v_lshlrev_b32_e32 v2, 1, v104
	v_writelane_b32 v255, s3, 40
	s_lshl_b64 s[2:3], s[40:41], 2
	v_pk_mul_f32 v[16:17], v[230:231], v[214:215] op_sel_hi:[0,1]
	v_pk_mul_f32 v[20:21], v[230:231], v[218:219] op_sel_hi:[0,1]
	v_pk_mul_f32 v[22:23], v[230:231], v[220:221] op_sel_hi:[0,1]
	v_pk_mul_f32 v[24:25], v[230:231], v[222:223] op_sel_hi:[0,1]
	v_pk_mul_f32 v[26:27], v[230:231], v[224:225] op_sel_hi:[0,1]
	v_pk_mul_f32 v[28:29], v[230:231], v[226:227] op_sel_hi:[0,1]
	v_pk_mul_f32 v[30:31], v[230:231], v[228:229] op_sel_hi:[0,1]
	v_and_b32_e32 v2, 32, v2
	v_lshlrev_b32_e32 v4, 4, v4
	v_lshlrev_b32_e32 v239, 4, v6
	v_sub_u32_e32 v6, v1, v3
	s_add_u32 s2, s58, s2
	v_fma_f32 v8, -v230, v236, v19
	v_fma_f32 v9, -v230, v236, v16
	v_fma_f32 v10, -v230, v236, v17
	v_fma_f32 v11, -v230, v236, v20
	v_fma_f32 v12, -v230, v236, v21
	v_fma_f32 v13, -v230, v236, v22
	v_fma_f32 v14, -v230, v236, v23
	v_fma_f32 v15, -v230, v236, v24
	v_fma_f32 v56, -v230, v236, v25
	v_fma_f32 v54, -v230, v236, v26
	v_fma_f32 v55, -v230, v236, v27
	v_fma_f32 v52, -v230, v236, v28
	v_fma_f32 v53, -v230, v236, v29
	v_fma_f32 v32, -v230, v236, v30
	v_fma_f32 v33, -v230, v236, v31
	v_or3_b32 v2, v5, v2, v4
	v_and_b32_e32 v242, 8, v66
	s_mov_b32 s5, 0
	v_cmp_gt_i32_e64 s[6:7], 0, v6
	v_cmp_gt_i32_e64 s[8:9], 1, v6
	v_cmp_gt_i32_e64 s[10:11], 2, v6
	v_cmp_gt_i32_e64 s[12:13], 3, v6
	v_cmp_gt_i32_e64 s[14:15], 8, v6
	v_cmp_gt_i32_e64 s[16:17], 9, v6
	v_cmp_gt_i32_e64 s[18:19], 10, v6
	v_cmp_gt_i32_e64 s[20:21], 11, v6
	v_cmp_gt_i32_e64 s[22:23], 16, v6
	v_cmp_gt_i32_e64 s[24:25], 17, v6
	v_cmp_gt_i32_e64 s[26:27], 18, v6
	v_cmp_gt_i32_e64 s[28:29], 19, v6
	v_cmp_gt_i32_e64 s[30:31], 24, v6
	v_cmp_gt_i32_e64 s[34:35], 25, v6
	v_cmp_gt_i32_e64 s[36:37], 26, v6
	v_cmp_gt_i32_e64 s[38:39], 27, v6
	v_cmp_lt_i32_e64 s[96:97], 0, v6
	v_cmp_lt_i32_e64 s[44:45], 1, v6
	v_cmp_lt_i32_e64 s[46:47], 2, v6
	v_cmp_lt_i32_e64 s[82:83], 3, v6
	v_cmp_lt_i32_e64 s[84:85], 8, v6
	v_cmp_lt_i32_e64 s[78:79], 9, v6
	v_cmp_lt_i32_e64 s[86:87], 10, v6
	v_cmp_lt_i32_e64 s[0:1], 11, v6
	v_cmp_lt_i32_e64 s[56:57], 16, v6
	s_addc_u32 s3, s59, s3
	v_cmp_lt_i32_e64 s[58:59], 17, v6
	v_cmp_lt_i32_e64 s[60:61], 18, v6
	v_xor_b32_e32 v34, 0x80000000, v18
	v_xor_b32_e32 v35, 0x80000000, v19
	v_xor_b32_e32 v36, 0x80000000, v20
	v_xor_b32_e32 v37, 0x80000000, v21
	v_xor_b32_e32 v38, 0x80000000, v22
	v_xor_b32_e32 v39, 0x80000000, v23
	v_xor_b32_e32 v40, 0x80000000, v24
	v_xor_b32_e32 v41, 0x80000000, v25
	v_xor_b32_e32 v42, 0x80000000, v26
	v_xor_b32_e32 v43, 0x80000000, v27
	v_xor_b32_e32 v44, 0x80000000, v28
	v_xor_b32_e32 v45, 0x80000000, v29
	v_xor_b32_e32 v46, 0x80000000, v30
	v_xor_b32_e32 v47, 0x80000000, v31
	v_and_b32_e32 v49, 0x7fffffff, v8
	v_and_b32_e32 v51, 0x7fffffff, v33
	v_and_b32_e32 v50, 0x7fffffff, v32
	v_xor_b32_e32 v33, 0x80000000, v17
	v_xor_b32_e32 v32, 0x80000000, v16
	v_add_u32_e32 v233, 0, v2
	v_sub_u32_e32 v245, 0xffffff80, v1
	v_add_u32_e32 v246, s4, v3
	v_sub_u32_e32 v247, 0xffffffc0, v1
	v_and_b32_e32 v53, 0x7fffffff, v53
	v_and_b32_e32 v52, 0x7fffffff, v52
	v_and_b32_e32 v55, 0x7fffffff, v55
	v_and_b32_e32 v54, 0x7fffffff, v54
	v_and_b32_e32 v57, 0x7fffffff, v56
	v_cmp_lt_i32_e64 s[62:63], 19, v6
	v_cmp_lt_i32_e64 s[64:65], 24, v6
	v_cmp_lt_i32_e64 s[66:67], 25, v6
	v_cmp_lt_i32_e64 s[68:69], 26, v6
	v_and_b32_e32 v56, 0x7fffffff, v15
	v_and_b32_e32 v59, 0x7fffffff, v14
	v_cmp_lt_i32_e64 s[70:71], 27, v6
	v_and_b32_e32 v58, 0x7fffffff, v13
	v_and_b32_e32 v61, 0x7fffffff, v12
	v_and_b32_e32 v60, 0x7fffffff, v11
	v_and_b32_e32 v63, 0x7fffffff, v10
	v_and_b32_e32 v62, 0x7fffffff, v9
	s_waitcnt lgkmcnt(0)
	s_barrier
; __device__ __forceinline__ void tab_load(const Frame& F, int row, int lane, f32x4 (&t)[8]) {
;     const float* s0 = (row < 16384 ? F.expert_u + (size_t)row * DM : F.expert_v + (size_t)(row - 16384) * DM) + 16 * lane;
; #pragma unroll
;     for (int q = 0; q < 8; ++q) t[q] = *(const f32x4*)(s0 + 1024 * (q >> 2) + 4 * (q & 3));
; }
	v_readlane_b32 s98, v254, 51
	v_readlane_b32 s99, v254, 30
	v_readlane_b32 s100, v254, 53
	s_nop 3
	s_cmp_lt_u32 s98, 3
	s_cbranch_scc1 .Lpf_done
	s_add_i32 s98, s98, 1
	s_lshl_b32 s99, s99, 3
	s_and_b32 s99, s99, -16
	s_or_b32 s99, s99, s100
	s_and_b32 s100, s98, 7
	s_or_b32 s99, s99, s100
	s_lshl_b32 s99, s99, 13
	v_mbcnt_lo_u32_b32 v192, -1, 0
	v_mbcnt_hi_u32_b32 v192, -1, v192
	v_lshlrev_b32_e32 v192, 6, v192
	s_cmp_lt_u32 s98, 16
	s_cbranch_scc1 .Lpf_real
	s_mov_b32 s99, 0
	v_mov_b32_e32 v192, 0
	s_mov_b32 s98, 0
.Lpf_real:
	s_cmp_lt_u32 s98, 8
	s_cbranch_scc0 .Lpf_v
	v_readlane_b32 s100, v255, 21
	v_readlane_b32 s101, v255, 22
	s_branch .Lpf_go
.Lpf_v:
	v_readlane_b32 s100, v255, 23
	v_readlane_b32 s101, v255, 24
.Lpf_go:
	s_nop 3
	s_add_u32 s100, s100, s99
	s_addc_u32 s101, s101, 0
	global_load_dwordx4 v[152:155], v192, s[100:101]
	global_load_dwordx4 v[156:159], v192, s[100:101] offset:16
	global_load_dwordx4 v[160:163], v192, s[100:101] offset:32
	global_load_dwordx4 v[164:167], v192, s[100:101] offset:48
	s_add_u32 s100, s100, 0x1000
	s_addc_u32 s101, s101, 0
	global_load_dwordx4 v[168:171], v192, s[100:101]
	global_load_dwordx4 v[172:175], v192, s[100:101] offset:16
	global_load_dwordx4 v[196:199], v192, s[100:101] offset:32
	global_load_dwordx4 v[200:203], v192, s[100:101] offset:48
.Lpf_done:
	s_branch .LBB0_309
.LBB0_307:
	s_or_b64 exec, exec, s[76:77]

; __device__ __forceinline__ unsigned pk2(float lo, float hi) { const f32x2 v = {lo, hi}; return __builtin_bit_cast(unsigned, __builtin_convertvector(v, bf16x2_t)); }
;     ...
;             float tmax = fmaxf(fmaxf(s[0], s[1]), s[2]);
; #pragma unroll
;             for (int reg = 3; reg < 15; reg += 2) tmax = fmaxf(fmaxf(tmax, s[reg]), s[reg + 1]);
;             tmax = fmaxf(tmax, s[15]) + cj;
;             tmax = fmaxf(tmax, __shfl_xor(tmax, 32));
;             if (__any(tmax > m + 8.0f)) { const float mnew = fmaxf(m, tmax); const float alpha = __builtin_amdgcn_exp2f(m - mnew); lsum *= alpha; m = mnew;
; #pragma unroll
;                 for (int reg = 0; reg < 16; ++reg) { o0[reg] *= alpha; o1[reg] *= alpha; } }
;             const float dd = cj - m;
;             f32x2 ps2 = {0.f, 0.f}; const f32x2 dd2 = {dd, dd};
; #pragma unroll
;             for (int rp = 0; rp < 8; ++rp) { f32x2 t; { const f32x2 in_ = {s[2 * rp], s[2 * rp + 1]}; asm("v_pk_add_f32 %0, %1, %2" : "=v"(t) : "v"(in_), "v"(dd2)); } t[0] = __builtin_amdgcn_exp2f(t[0]); t[1] = __builtin_amdgcn_exp2f(t[1]); s[2 * rp] = t[0]; s[2 * rp + 1] = t[1]; asm("v_pk_add_f32 %0, %1, %2" : "=v"(ps2) : "v"(ps2), "v"(t)); }
;             lsum += ps2[0] + ps2[1];
;             bf16x8 pf[2];
; #pragma unroll
;             for (int st = 0; st < 2; ++st) { v4u t; t.x = pk2(s[8 * st + 0], s[8 * st + 1]); t.y = pk2(s[8 * st + 2], s[8 * st + 3]); t.z = pk2(s[8 * st + 4], s[8 * st + 5]); t.w = pk2(s[8 * st + 6], s[8 * st + 7]); pf[st] = __builtin_bit_cast(bf16x8, t); }
; #pragma unroll
;             for (int st = 0; st < 2; ++st) {
;                 const bf16x8 v0 = (bf16x8){vlo[0][st][0], vlo[0][st][1], vlo[0][st][2], vlo[0][st][3], vhi[0][st][0], vhi[0][st][1], vhi[0][st][2], vhi[0][st][3]};
;                 const bf16x8 v1 = (bf16x8){vlo[1][st][0], vlo[1][st][1], vlo[1][st][2], vlo[1][st][3], vhi[1][st][0], vhi[1][st][1], vhi[1][st][2], vhi[1][st][3]};
;                 o0 = __builtin_amdgcn_mfma_f32_32x32x16_bf16(v0, pf[st], o0, 0, 0, 0);
;                 o1 = __builtin_amdgcn_mfma_f32_32x32x16_bf16(v1, pf[st], o1, 0, 0, 0); }
.LBB0_334:
	v_max_f32_e32 v14, v145, v145
	v_max_f32_e32 v15, v144, v144
	v_max_f32_e32 v14, v15, v14
	v_max3_f32 v14, v14, v146, v147
	v_max3_f32 v14, v14, v148, v149
	v_max3_f32 v14, v14, v150, v151
	v_max3_f32 v14, v14, v152, v153
	v_max3_f32 v14, v14, v154, v155
	v_max3_f32 v14, v14, v156, v157
	v_max3_f32 v14, v14, v158, v159
	v_add_f32_e32 v14, v1, v14
	v_mov_b32_e32 v15, v14
	s_nop 1
	v_permlane32_swap_b32_e32 v14, v15
	v_max_f32_e32 v14, v14, v15
	v_add_f32_e32 v15, 0x41000000, v252
	v_cmp_gt_f32_e32 vcc, v14, v15
	s_cbranch_vccz .LBB0_336
	v_max_f32_e32 v14, v14, v14
	v_max_f32_e32 v15, v252, v252
	v_max_f32_e32 v15, v15, v14
	v_sub_f32_e32 v14, v252, v15
	v_exp_f32_e32 v14, v14
	v_mov_b32_e32 v252, v15
	v_pk_mul_f32 v[94:95], v[94:95], v[14:15] op_sel_hi:[1,0]
	v_pk_mul_f32 v[92:93], v[92:93], v[14:15] op_sel_hi:[1,0]
	v_pk_mul_f32 v[90:91], v[90:91], v[14:15] op_sel_hi:[1,0]
	v_pk_mul_f32 v[88:89], v[88:89], v[14:15] op_sel_hi:[1,0]
	v_pk_mul_f32 v[86:87], v[86:87], v[14:15] op_sel_hi:[1,0]
	v_pk_mul_f32 v[84:85], v[84:85], v[14:15] op_sel_hi:[1,0]
	v_pk_mul_f32 v[82:83], v[82:83], v[14:15] op_sel_hi:[1,0]
	v_pk_mul_f32 v[80:81], v[80:81], v[14:15] op_sel_hi:[1,0]
	v_pk_mul_f32 v[78:79], v[78:79], v[14:15] op_sel_hi:[1,0]
	v_pk_mul_f32 v[76:77], v[76:77], v[14:15] op_sel_hi:[1,0]
	v_pk_mul_f32 v[74:75], v[74:75], v[14:15] op_sel_hi:[1,0]
	v_pk_mul_f32 v[72:73], v[72:73], v[14:15] op_sel_hi:[1,0]
	v_pk_mul_f32 v[70:71], v[70:71], v[14:15] op_sel_hi:[1,0]
	v_pk_mul_f32 v[68:69], v[68:69], v[14:15] op_sel_hi:[1,0]
	v_pk_mul_f32 v[66:67], v[66:67], v[14:15] op_sel_hi:[1,0]
	v_pk_mul_f32 v[64:65], v[64:65], v[14:15] op_sel_hi:[1,0]
	v_mul_f32_e32 v253, v253, v14
.LBB0_336:
	v_sub_f32_e32 v14, v1, v252
	v_mov_b32_e32 v15, v14
	v_pk_add_f32 v[144:145], v[144:145], v[14:15]
	v_pk_add_f32 v[146:147], v[146:147], v[14:15]
	v_pk_add_f32 v[148:149], v[148:149], v[14:15]
	v_pk_add_f32 v[150:151], v[150:151], v[14:15]
	v_mov_b32_e32 v1, v0
	v_exp_f32_e32 v144, v144
	v_exp_f32_e32 v145, v145
	v_exp_f32_e32 v146, v146
	v_exp_f32_e32 v147, v147
	v_exp_f32_e32 v148, v148
	v_exp_f32_e32 v149, v149
	v_exp_f32_e32 v150, v150
	v_exp_f32_e32 v151, v151
	v_pk_add_f32 v[160:161], v[0:1], v[144:145]
	v_cvt_pk_bf16_f32 v144, v144, v145
	v_pk_add_f32 v[160:161], v[160:161], v[146:147]
	v_cvt_pk_bf16_f32 v145, v146, v147
	v_cvt_pk_bf16_f32 v146, v148, v149
	v_cvt_pk_bf16_f32 v147, v150, v151
	v_pk_add_f32 v[152:153], v[152:153], v[14:15]
	v_pk_add_f32 v[154:155], v[154:155], v[14:15]
	v_pk_add_f32 v[156:157], v[156:157], v[14:15]
	s_nop 0
	v_exp_f32_e32 v152, v152
	s_waitcnt lgkmcnt(0)
	v_mfma_f32_32x32x16_bf16 v[80:95], v[208:211], v[144:147], v[80:95]
	v_exp_f32_e32 v153, v153
	v_exp_f32_e32 v154, v154
	v_exp_f32_e32 v155, v155
	v_exp_f32_e32 v156, v156
	v_exp_f32_e32 v157, v157
	v_mfma_f32_32x32x16_bf16 v[64:79], v[10:13], v[144:147], v[64:79]
	v_pk_add_f32 v[10:11], v[158:159], v[14:15]
	v_cvt_pk_bf16_f32 v12, v156, v157
	v_exp_f32_e32 v14, v10
	v_exp_f32_e32 v15, v11
	v_cvt_pk_bf16_f32 v10, v152, v153
	v_cvt_pk_bf16_f32 v11, v154, v155
	v_cvt_pk_bf16_f32 v13, v14, v15
	s_nop 1
	v_mfma_f32_32x32x16_bf16 v[80:95], v[6:9], v[10:13], v[80:95]
	v_pk_add_f32 v[6:7], v[160:161], v[148:149]
	s_nop 0
	v_pk_add_f32 v[6:7], v[6:7], v[150:151]
	s_nop 0
	v_pk_add_f32 v[6:7], v[6:7], v[152:153]
	s_nop 0
	v_pk_add_f32 v[6:7], v[6:7], v[154:155]
	v_mfma_f32_32x32x16_bf16 v[64:79], v[2:5], v[10:13], v[64:79]
	v_pk_add_f32 v[6:7], v[6:7], v[156:157]
	s_nop 0
	v_pk_add_f32 v[6:7], v[6:7], v[14:15]
	s_nop 0
	v_add_f32_e32 v1, v6, v7
	v_add_f32_e32 v253, v253, v1
	s_branch .LBB0_338

; #define LAS __attribute__((address_space(3)))
;     ...
;             s16x4 vlo[2][2], vhi[2][2];
; #pragma unroll
;             for (int st = 0; st < 2; ++st) {
;                 vlo[0][st] = __builtin_bit_cast(s16x4, __builtin_amdgcn_ds_read_tr16_b64_v4i16((LAS s16x4*)(vb0 + 4096 * j + 2048 * st)));
;                 vhi[0][st] = __builtin_bit_cast(s16x4, __builtin_amdgcn_ds_read_tr16_b64_v4i16((LAS s16x4*)(vb0 + 4096 * j + 2048 * st + 1024)));
;                 vlo[1][st] = __builtin_bit_cast(s16x4, __builtin_amdgcn_ds_read_tr16_b64_v4i16((LAS s16x4*)(vb1 + 4096 * j + 2048 * st)));
;                 vhi[1][st] = __builtin_bit_cast(s16x4, __builtin_amdgcn_ds_read_tr16_b64_v4i16((LAS s16x4*)(vb1 + 4096 * j + 2048 * st + 1024))); }
;             f32x16 s; float cj;
;             const float cl = slope2 * (float)(32 * j - HALFW - ql);
;             if (j < JM) { s = __builtin_amdgcn_mfma_f32_32x32x16_bf16(kf[0], qf[0], CL, 0, 0, 0); cj = cl; }
;             else if (j == JM) { s = __builtin_amdgcn_mfma_f32_32x32x16_bf16(kf[0], qf[0], CM, 0, 0, 0); cj = 0.f; }
;             else { s = __builtin_amdgcn_mfma_f32_32x32x16_bf16(kf[0], qf[0], CR, 0, 0, 0); cj = -cl; }
; #pragma unroll
;             for (int ks = 1; ks < 4; ++ks) s = __builtin_amdgcn_mfma_f32_32x32x16_bf16(kf[ks], qf[ks], s, 0, 0, 0);
.LBB0_345:
	s_andn2_b64 vcc, exec, s[76:77]
	s_cbranch_vccnz .LBB0_367
	v_add_u32_e32 v1, v150, v242
	s_waitcnt lgkmcnt(3)
	v_add_u32_e32 v2, 0x10000, v1
	v_add_u32_e32 v3, v151, v242
	ds_read_b64_tr_b16 v[144:145], v2
	v_add_u32_e32 v2, 0x10400, v1
	v_add_u32_e32 v4, 0x10000, v3
	ds_read_b64_tr_b16 v[146:147], v2
	s_waitcnt lgkmcnt(3)
	ds_read_b64_tr_b16 v[10:11], v4
	v_add_u32_e32 v2, 0x10400, v3
	ds_read_b64_tr_b16 v[12:13], v2
	v_add_u32_e32 v2, 0x10800, v1
	v_add_u32_e32 v1, 0x10c00, v1
	ds_read_b64_tr_b16 v[6:7], v2
	ds_read_b64_tr_b16 v[8:9], v1
	v_add_u32_e32 v1, 0x10800, v3
	v_add_u32_e32 v4, 0x10c00, v3
	v_add_u32_e32 v2, s91, v247
	v_cvt_f32_i32_e32 v15, v2
	ds_read_b64_tr_b16 v[2:3], v1
	ds_read_b64_tr_b16 v[4:5], v4
	s_cmp_gt_u32 s93, 1
	s_mov_b64 s[76:77], -1
	v_mul_f32_e32 v15, v230, v15
	s_cbranch_scc0 .LBB0_352
	s_cmp_lg_u32 s91, 64
	s_cbranch_scc0 .LBB0_349
	v_xor_b32_e32 v1, 0x80000000, v15
	s_mov_b64 s[76:77], 0
	s_waitcnt vmcnt(11)
	v_mfma_f32_32x32x16_bf16 v[112:127], v[140:143], v[176:179], v[32:47]
.LBB0_349:
	s_andn2_b64 vcc, exec, s[76:77]
	s_cbranch_vccnz .LBB0_351
	s_nop 9
	v_xor_b32_e32 v127, 0x80000000, v51
	v_xor_b32_e32 v126, 0x80000000, v50
	v_xor_b32_e32 v125, 0x80000000, v53
	v_xor_b32_e32 v124, 0x80000000, v52
	v_xor_b32_e32 v123, 0x80000000, v55
	v_xor_b32_e32 v122, 0x80000000, v54
	v_xor_b32_e32 v121, 0x80000000, v57
	v_xor_b32_e32 v120, 0x80000000, v56
	v_xor_b32_e32 v119, 0x80000000, v59
	v_xor_b32_e32 v118, 0x80000000, v58
	v_xor_b32_e32 v117, 0x80000000, v61
	v_xor_b32_e32 v116, 0x80000000, v60
	v_xor_b32_e32 v115, 0x80000000, v49
	v_xor_b32_e32 v114, 0x80000000, v48
	v_xor_b32_e32 v113, 0x80000000, v63
	v_xor_b32_e32 v112, 0x80000000, v62
	v_mov_b32_e32 v1, 0
	s_waitcnt vmcnt(11)
	v_mfma_f32_32x32x16_bf16 v[112:127], v[140:143], v[176:179], v[112:127]

; #define LAS __attribute__((address_space(3)))
;     ...
;             if (j < JM) { s = __builtin_amdgcn_mfma_f32_32x32x16_bf16(kf[0], qf[0], CL, 0, 0, 0); cj = cl; }
;             else if (j == JM) { s = __builtin_amdgcn_mfma_f32_32x32x16_bf16(kf[0], qf[0], CM, 0, 0, 0); cj = 0.f; }
;             else { s = __builtin_amdgcn_mfma_f32_32x32x16_bf16(kf[0], qf[0], CR, 0, 0, 0); cj = -cl; }
; #pragma unroll
;             for (int ks = 1; ks < 4; ++ks) s = __builtin_amdgcn_mfma_f32_32x32x16_bf16(kf[ks], qf[ks], s, 0, 0, 0);
; #pragma unroll
;             for (int ks = 0; ks < 4; ++ks) kf[ks] = *(const LAS bf16x8*)(kb + 4096 * jn + koff[ks]);
;             if (j == 0) {
; #pragma unroll
;                 for (int reg = 0; reg < 16; ++reg) s[reg] = ((reg & 3) + 8 * (reg >> 2) >= ql4) ? s[reg] : -INFINITY;
;             } else if (j == NTILE - 1) {
; #pragma unroll
;                 for (int reg = 0; reg < 16; ++reg) s[reg] = ((reg & 3) + 8 * (reg >> 2) <= ql4) ? s[reg] : -INFINITY;
.LBB0_352:
	s_andn2_b64 vcc, exec, s[76:77]
	s_cbranch_vccnz .LBB0_354
	s_waitcnt vmcnt(11)
	v_mfma_f32_32x32x16_bf16 v[112:127], v[140:143], v[176:179], v[16:31]
	v_mov_b32_e32 v1, v15
.LBB0_354:
	s_waitcnt vmcnt(10)
	v_mfma_f32_32x32x16_bf16 v[112:127], v[136:139], v[180:183], v[112:127]
	v_add_u32_e32 v15, v14, v237
	s_waitcnt lgkmcnt(8)
	v_add_u32_e32 v96, v14, v238
	ds_read_b128 v[140:143], v15
	ds_read_b128 v[136:139], v96
	v_add_u32_e32 v15, v14, v239
	v_add_u32_e32 v14, v14, v240
	s_cmp_lt_i32 s93, 4
	s_mov_b64 s[76:77], -1
	s_waitcnt vmcnt(9)
	v_mfma_f32_32x32x16_bf16 v[112:127], v[132:135], v[184:187], v[112:127]
	s_waitcnt vmcnt(8)
	v_mfma_f32_32x32x16_bf16 v[112:127], v[128:131], v[188:191], v[112:127]
	ds_read_b128 v[132:135], v15
	ds_read_b128 v[128:131], v14
	s_cbranch_scc1 .LBB0_358
	s_nop 8
	v_mov_b64_e32 v[96:97], v[112:113]
	s_cmp_eq_u32 s93, 4
	v_mov_b64_e32 v[98:99], v[114:115]
	v_mov_b64_e32 v[100:101], v[116:117]
	v_mov_b64_e32 v[102:103], v[118:119]
	v_mov_b64_e32 v[104:105], v[120:121]
	v_mov_b64_e32 v[106:107], v[122:123]
	v_mov_b64_e32 v[108:109], v[124:125]
	v_mov_b64_e32 v[110:111], v[126:127]
	s_cbranch_scc0 .LBB0_357
	v_cndmask_b32_e64 v96, v112, v235, s[6:7]
	v_cndmask_b32_e64 v97, v113, v235, s[8:9]
	v_cndmask_b32_e64 v98, v114, v235, s[10:11]
	v_cndmask_b32_e64 v99, v115, v235, s[12:13]
	v_cndmask_b32_e64 v100, v116, v235, s[14:15]
	v_cndmask_b32_e64 v101, v117, v235, s[16:17]
	v_cndmask_b32_e64 v102, v118, v235, s[18:19]
	v_cndmask_b32_e64 v103, v119, v235, s[20:21]
	v_cndmask_b32_e64 v104, v120, v235, s[22:23]
	v_cndmask_b32_e64 v105, v121, v235, s[24:25]
	v_cndmask_b32_e64 v106, v122, v235, s[26:27]
	v_cndmask_b32_e64 v107, v123, v235, s[28:29]
	v_cndmask_b32_e64 v108, v124, v235, s[30:31]
	v_cndmask_b32_e64 v109, v125, v235, s[34:35]
	v_cndmask_b32_e64 v110, v126, v235, s[36:37]
	v_cndmask_b32_e64 v111, v127, v235, s[38:39]

; __device__ __forceinline__ unsigned pk2(float lo, float hi) { const f32x2 v = {lo, hi}; return __builtin_bit_cast(unsigned, __builtin_convertvector(v, bf16x2_t)); }
;     ...
;             float tmax = fmaxf(fmaxf(s[0], s[1]), s[2]);
; #pragma unroll
;             for (int reg = 3; reg < 15; reg += 2) tmax = fmaxf(fmaxf(tmax, s[reg]), s[reg + 1]);
;             tmax = fmaxf(tmax, s[15]) + cj;
;             tmax = fmaxf(tmax, __shfl_xor(tmax, 32));
;             if (__any(tmax > m + 8.0f)) { const float mnew = fmaxf(m, tmax); const float alpha = __builtin_amdgcn_exp2f(m - mnew); lsum *= alpha; m = mnew;
; #pragma unroll
;                 for (int reg = 0; reg < 16; ++reg) { o0[reg] *= alpha; o1[reg] *= alpha; } }
;             const float dd = cj - m;
;             f32x2 ps2 = {0.f, 0.f}; const f32x2 dd2 = {dd, dd};
; #pragma unroll
;             for (int rp = 0; rp < 8; ++rp) { f32x2 t; { const f32x2 in_ = {s[2 * rp], s[2 * rp + 1]}; asm("v_pk_add_f32 %0, %1, %2" : "=v"(t) : "v"(in_), "v"(dd2)); } t[0] = __builtin_amdgcn_exp2f(t[0]); t[1] = __builtin_amdgcn_exp2f(t[1]); s[2 * rp] = t[0]; s[2 * rp + 1] = t[1]; asm("v_pk_add_f32 %0, %1, %2" : "=v"(ps2) : "v"(ps2), "v"(t)); }
;             lsum += ps2[0] + ps2[1];
;             bf16x8 pf[2];
; #pragma unroll
;             for (int st = 0; st < 2; ++st) { v4u t; t.x = pk2(s[8 * st + 0], s[8 * st + 1]); t.y = pk2(s[8 * st + 2], s[8 * st + 3]); t.z = pk2(s[8 * st + 4], s[8 * st + 5]); t.w = pk2(s[8 * st + 6], s[8 * st + 7]); pf[st] = __builtin_bit_cast(bf16x8, t); }
; #pragma unroll
;             for (int st = 0; st < 2; ++st) {
;                 const bf16x8 v0 = (bf16x8){vlo[0][st][0], vlo[0][st][1], vlo[0][st][2], vlo[0][st][3], vhi[0][st][0], vhi[0][st][1], vhi[0][st][2], vhi[0][st][3]};
;                 const bf16x8 v1 = (bf16x8){vlo[1][st][0], vlo[1][st][1], vlo[1][st][2], vlo[1][st][3], vhi[1][st][0], vhi[1][st][1], vhi[1][st][2], vhi[1][st][3]};
;                 o0 = __builtin_amdgcn_mfma_f32_32x32x16_bf16(v0, pf[st], o0, 0, 0, 0);
;                 o1 = __builtin_amdgcn_mfma_f32_32x32x16_bf16(v1, pf[st], o1, 0, 0, 0); }
.LBB0_364:
	v_max_f32_e32 v14, v97, v97
	v_max_f32_e32 v15, v96, v96
	v_max_f32_e32 v14, v15, v14
	v_max3_f32 v14, v14, v98, v99
	v_max3_f32 v14, v14, v100, v101
	v_max3_f32 v14, v14, v102, v103
	v_max3_f32 v14, v14, v104, v105
	v_max3_f32 v14, v14, v106, v107
	v_max3_f32 v14, v14, v108, v109
	v_max3_f32 v14, v14, v110, v111
	v_add_f32_e32 v14, v1, v14
	v_mov_b32_e32 v15, v14
	s_nop 1
	v_permlane32_swap_b32_e32 v14, v15
	v_max_f32_e32 v14, v14, v15
	v_add_f32_e32 v15, 0x41000000, v148
	v_cmp_gt_f32_e32 vcc, v14, v15
	s_cbranch_vccz .LBB0_366
	v_max_f32_e32 v14, v14, v14
	v_max_f32_e32 v15, v148, v148
	v_max_f32_e32 v15, v15, v14
	v_sub_f32_e32 v14, v148, v15
	v_exp_f32_e32 v14, v14
	v_mov_b32_e32 v148, v15
	v_pk_mul_f32 v[94:95], v[94:95], v[14:15] op_sel_hi:[1,0]
	v_pk_mul_f32 v[92:93], v[92:93], v[14:15] op_sel_hi:[1,0]
	v_pk_mul_f32 v[90:91], v[90:91], v[14:15] op_sel_hi:[1,0]
	v_pk_mul_f32 v[88:89], v[88:89], v[14:15] op_sel_hi:[1,0]
	v_pk_mul_f32 v[86:87], v[86:87], v[14:15] op_sel_hi:[1,0]
	v_pk_mul_f32 v[84:85], v[84:85], v[14:15] op_sel_hi:[1,0]
	v_pk_mul_f32 v[82:83], v[82:83], v[14:15] op_sel_hi:[1,0]
	v_pk_mul_f32 v[80:81], v[80:81], v[14:15] op_sel_hi:[1,0]
	v_pk_mul_f32 v[78:79], v[78:79], v[14:15] op_sel_hi:[1,0]
	v_pk_mul_f32 v[76:77], v[76:77], v[14:15] op_sel_hi:[1,0]
	v_pk_mul_f32 v[74:75], v[74:75], v[14:15] op_sel_hi:[1,0]
	v_pk_mul_f32 v[72:73], v[72:73], v[14:15] op_sel_hi:[1,0]
	v_pk_mul_f32 v[70:71], v[70:71], v[14:15] op_sel_hi:[1,0]
	v_pk_mul_f32 v[68:69], v[68:69], v[14:15] op_sel_hi:[1,0]
	v_pk_mul_f32 v[66:67], v[66:67], v[14:15] op_sel_hi:[1,0]
	v_pk_mul_f32 v[64:65], v[64:65], v[14:15] op_sel_hi:[1,0]
	v_mul_f32_e32 v149, v149, v14
.LBB0_366:
	v_sub_f32_e32 v14, v1, v148
	v_mov_b32_e32 v15, v14
	v_pk_add_f32 v[96:97], v[96:97], v[14:15]
	v_pk_add_f32 v[98:99], v[98:99], v[14:15]
	v_pk_add_f32 v[100:101], v[100:101], v[14:15]
	v_pk_add_f32 v[102:103], v[102:103], v[14:15]
	v_mov_b32_e32 v1, v0
	v_exp_f32_e32 v96, v96
	v_exp_f32_e32 v97, v97
	v_exp_f32_e32 v98, v98
	v_exp_f32_e32 v99, v99
	v_exp_f32_e32 v100, v100
	v_exp_f32_e32 v101, v101
	v_exp_f32_e32 v102, v102
	v_exp_f32_e32 v103, v103
	v_pk_add_f32 v[112:113], v[0:1], v[96:97]
	v_cvt_pk_bf16_f32 v96, v96, v97
	v_pk_add_f32 v[112:113], v[112:113], v[98:99]
	v_cvt_pk_bf16_f32 v97, v98, v99
	v_cvt_pk_bf16_f32 v98, v100, v101
	v_cvt_pk_bf16_f32 v99, v102, v103
	v_pk_add_f32 v[104:105], v[104:105], v[14:15]
	v_pk_add_f32 v[106:107], v[106:107], v[14:15]
	v_pk_add_f32 v[108:109], v[108:109], v[14:15]
	s_nop 0
	v_exp_f32_e32 v104, v104
	s_waitcnt lgkmcnt(0)
	v_mfma_f32_32x32x16_bf16 v[80:95], v[144:147], v[96:99], v[80:95]
	v_exp_f32_e32 v105, v105
	v_exp_f32_e32 v106, v106
	v_exp_f32_e32 v107, v107
	v_exp_f32_e32 v108, v108
	v_exp_f32_e32 v109, v109
	v_mfma_f32_32x32x16_bf16 v[64:79], v[10:13], v[96:99], v[64:79]
	v_pk_add_f32 v[10:11], v[110:111], v[14:15]
	v_cvt_pk_bf16_f32 v12, v108, v109
	v_exp_f32_e32 v14, v10
	v_exp_f32_e32 v15, v11
	v_cvt_pk_bf16_f32 v10, v104, v105
	v_cvt_pk_bf16_f32 v11, v106, v107
	v_cvt_pk_bf16_f32 v13, v14, v15
	s_nop 1
	v_mfma_f32_32x32x16_bf16 v[80:95], v[6:9], v[10:13], v[80:95]
	v_pk_add_f32 v[6:7], v[112:113], v[100:101]
	s_nop 0
	v_pk_add_f32 v[6:7], v[6:7], v[102:103]
	s_nop 0
	v_pk_add_f32 v[6:7], v[6:7], v[104:105]
	s_nop 0
	v_pk_add_f32 v[6:7], v[6:7], v[106:107]
	v_mfma_f32_32x32x16_bf16 v[64:79], v[2:5], v[10:13], v[64:79]
	v_pk_add_f32 v[6:7], v[6:7], v[108:109]
	s_nop 0
	v_pk_add_f32 v[6:7], v[6:7], v[14:15]
	s_nop 0
	v_add_f32_e32 v1, v6, v7
	v_add_f32_e32 v149, v149, v1
	s_branch .LBB0_368

; #define LAS __attribute__((address_space(3)))
; __global__ void __launch_bounds__(NTHREADS, 2) hymba_fwd(Args args) {
;     extern __shared__ __attribute__((aligned(16))) unsigned char lds[];
;     Frame F;
;     F.lds = (LAS unsigned char*)lds; F.lds_g = lds;
;     F.tid = threadIdx.x; F.lane = F.tid & 63; F.wave = __builtin_amdgcn_readfirstlane(F.tid >> 6);
	.amdhsa_kernel _Z9hymba_fwd4Args
		.amdhsa_group_segment_fixed_size 0
		.amdhsa_private_segment_fixed_size 0
		.amdhsa_kernarg_size 392
		.amdhsa_user_sgpr_count 2
		.amdhsa_user_sgpr_dispatch_ptr 0
		.amdhsa_user_sgpr_queue_ptr 0
		.amdhsa_user_sgpr_kernarg_segment_ptr 1
		.amdhsa_user_sgpr_dispatch_id 0
		.amdhsa_user_sgpr_kernarg_preload_length 0
		.amdhsa_user_sgpr_kernarg_preload_offset 0
		.amdhsa_user_sgpr_private_segment_size 0
		.amdhsa_uses_dynamic_stack 0
		.amdhsa_enable_private_segment 0
		.amdhsa_system_sgpr_workgroup_id_x 1
		.amdhsa_system_sgpr_workgroup_id_y 0
		.amdhsa_system_sgpr_workgroup_id_z 0
		.amdhsa_system_sgpr_workgroup_info 0
		.amdhsa_system_vgpr_workitem_id 0
		.amdhsa_next_free_vgpr 256
		.amdhsa_next_free_sgpr 102
		.amdhsa_accum_offset 256
		.amdhsa_reserve_vcc 1
		.amdhsa_float_round_mode_32 0
		.amdhsa_float_round_mode_16_64 0
		.amdhsa_float_denorm_mode_32 3
		.amdhsa_float_denorm_mode_16_64 3
		.amdhsa_dx10_clamp 1
		.amdhsa_ieee_mode 1
		.amdhsa_fp16_overflow 0
		.amdhsa_tg_split 0
		.amdhsa_exception_fp_ieee_invalid_op 0
		.amdhsa_exception_fp_denorm_src 0
		.amdhsa_exception_fp_ieee_div_zero 0
		.amdhsa_exception_fp_ieee_overflow 0
		.amdhsa_exception_fp_ieee_underflow 0
		.amdhsa_exception_fp_ieee_inexact 0
		.amdhsa_exception_int_div_zero 0
	.end_amdhsa_kernel

; #define LAS __attribute__((address_space(3)))
; __global__ void __launch_bounds__(NTHREADS, 2) hymba_fwd(Args args) {
;     extern __shared__ __attribute__((aligned(16))) unsigned char lds[];
;     Frame F;
;     F.lds = (LAS unsigned char*)lds; F.lds_g = lds;
;     F.tid = threadIdx.x; F.lane = F.tid & 63; F.wave = __builtin_amdgcn_readfirstlane(F.tid >> 6);
amdhsa.kernels:
  - .agpr_count:     0
    .args:
      - .offset:         0
        .size:           136
        .value_kind:     by_value
      - .offset:         136
        .size:           4
        .value_kind:     hidden_block_count_x
      - .offset:         140
        .size:           4
        .value_kind:     hidden_block_count_y
      - .offset:         144
        .size:           4
        .value_kind:     hidden_block_count_z
      - .offset:         148
        .size:           2
        .value_kind:     hidden_group_size_x
      - .offset:         150
        .size:           2
        .value_kind:     hidden_group_size_y
      - .offset:         152
        .size:           2
        .value_kind:     hidden_group_size_z
      - .offset:         154
        .size:           2
        .value_kind:     hidden_remainder_x
      - .offset:         156
        .size:           2
        .value_kind:     hidden_remainder_y
      - .offset:         158
        .size:           2
        .value_kind:     hidden_remainder_z
      - .offset:         176
        .size:           8
        .value_kind:     hidden_global_offset_x
      - .offset:         184
        .size:           8
        .value_kind:     hidden_global_offset_y
      - .offset:         192
        .size:           8
        .value_kind:     hidden_global_offset_z
      - .offset:         200
        .size:           2
        .value_kind:     hidden_grid_dims
      - .offset:         256
        .size:           4
        .value_kind:     hidden_dynamic_lds_size
    .group_segment_fixed_size: 0
    .kernarg_segment_align: 8
    .kernarg_segment_size: 392
    .language:       OpenCL C
    .language_version:
      - 2
      - 0
    .max_flat_workgroup_size: 512
    .name:           _Z9hymba_fwd4Args
    .private_segment_fixed_size: 0
    .sgpr_count:     108
    .sgpr_spill_count: 157
    .symbol:         _Z9hymba_fwd4Args.kd
    .uniform_work_group_size: 1
    .uses_dynamic_stack: false
    .vgpr_count:     256
    .vgpr_spill_count: 0
    .wavefront_size: 64
